# 32-byte entry pad, second sample
# speedup vs baseline: 1.0021x; 1.0021x over previous
_Z10fwd_kernel6Params:
	s_nop 0
	s_nop 0
	s_nop 0
	s_nop 0
	s_nop 0
	s_nop 0
	s_nop 0
	s_nop 0
	s_load_dwordx8 s[12:19], s[0:1], 0x1a0
	s_load_dwordx8 s[4:11], s[0:1], 0x180
	v_and_b32_e32 v220, 0x3ff, v0
	v_writelane_b32 v252, s2, 0
	s_waitcnt lgkmcnt(0)
	v_writelane_b32 v252, s4, 1
	s_nop 1
	v_writelane_b32 v252, s5, 2
	v_writelane_b32 v252, s6, 3
	v_writelane_b32 v252, s7, 4
	v_writelane_b32 v252, s8, 5
	v_writelane_b32 v252, s9, 6
	v_writelane_b32 v252, s10, 7
	v_writelane_b32 v252, s11, 8
	v_cmp_eq_u32_e64 s[4:5], 0, v220
	s_mov_b64 s[2:3], exec
	s_nop 0
	v_writelane_b32 v252, s4, 9
	s_nop 1
	v_writelane_b32 v252, s5, 10
	s_and_b64 s[4:5], s[2:3], s[4:5]
	s_mov_b64 exec, s[4:5]
	v_mov_b32_e32 v2, 0
	v_mov_b32_e32 v3, v2
	v_mov_b32_e32 v4, v2
	v_mov_b32_e32 v5, v2
	ds_write_b128 v2, v[2:5]
	s_or_b64 exec, exec, s[2:3]
	s_waitcnt lgkmcnt(0)
	s_barrier
	s_getreg_b32 s2, hwreg(HW_REG_XCC_ID, 0, 4)
	s_and_b32 s6, s2, 15
	s_mov_b64 s[2:3], exec
	v_readlane_b32 s4, v252, 9
	v_readlane_b32 s5, v252, 10
	s_and_b64 s[4:5], s[2:3], s[4:5]
	s_mov_b64 exec, s[4:5]
	s_cbranch_execz .LBB0_5
	s_mov_b64 s[4:5], exec
	v_mbcnt_lo_u32_b32 v1, s4, 0
	v_mbcnt_hi_u32_b32 v1, s5, v1
	v_cmp_eq_u32_e32 vcc, 0, v1
	s_and_b64 s[8:9], exec, vcc
	s_mov_b64 exec, s[8:9]
	s_cbranch_execz .LBB0_5
	s_lshl_b32 s7, s6, 8
	s_bcnt1_i32_b64 s4, s[4:5]
	v_mov_b32_e32 v1, s7
	v_mov_b32_e32 v2, s4
	global_atomic_add v1, v2, s[14:15] offset:1280
